# memory cross-attention through LDS: 16-stage ring, 14 tiles of DMA lookahead, two tiles per barrier with the two MFMA chains interleaved
# speedup vs baseline: 1.0124x; 1.0031x over previous
; __device__ __forceinline__ f32x4 mfma16(bf16x8 a, bf16x8 b, f32x4 c) { return __builtin_amdgcn_mfma_f32_16x16x32_bf16(a, b, c, 0, 0, 0); }
; __device__ __forceinline__ void mem_task(bf16_t* zb, const bf16_t* kvm_b, const bf16_t* vmt_b, int hm, int t0, int lane, bool do_store) {
;     const int n = lane & 15, fq = lane >> 4;
;     bf16_t* qp = zb + (size_t)(t0 + n) * ZM + ZC_QM + hm * 256;
;     bf16x8 qf[8];
; #pragma unroll
;     for (int kk = 0; kk < 8; ++kk) qf[kk] = *(const bf16x8*)(qp + kk * 32 + 8 * fq);
;     f32x4 zero4 = {0.f, 0.f, 0.f, 0.f}; asm volatile("" : "+v"(zero4));
;     f32x4 s[16];
;     const bf16_t* kbase = kvm_b + (size_t)(8 * (n >> 2) + (n & 3)) * 2048 + hm * 256 + 8 * fq;
;     bf16x8 kfr[3][8];
; #pragma unroll
;     for (int kk = 0; kk < 8; ++kk) kfr[0][kk] = *(const bf16x8*)(kbase + kk * 32);
;     { const bf16_t* kp = kbase + (size_t)4 * 2048;
; #pragma unroll
;       for (int kk = 0; kk < 8; ++kk) kfr[1][kk] = *(const bf16x8*)(kp + kk * 32); }
; #pragma unroll
;     for (int kt = 0; kt < 16; ++kt) {
;         if (kt + 2 < 16) { const bf16_t* kp = kbase + (size_t)(((kt + 2) >> 1) * 32 + 4 * ((kt + 2) & 1)) * 2048;
; #pragma unroll
;             for (int kk = 0; kk < 8; ++kk) kfr[(kt + 2) % 3][kk] = *(const bf16x8*)(kp + kk * 32); }
;         f32x4 acc = zero4;
;         __builtin_amdgcn_s_setprio(1);
; #pragma unroll
;         for (int kk = 0; kk < 8; ++kk) acc = mfma16(kfr[kt % 3][kk], qf[kk], acc);
;         __builtin_amdgcn_s_setprio(0);
;         s[kt] = acc; }
.LBB0_366:
	v_and_or_b32 v186, s0, -16, v65
	v_mov_b64_e32 v[188:189], s[78:79]
	s_and_b32 s2, s3, 0x300
	v_mad_i64_i32 v[188:189], s[6:7], v186, s11, v[188:189]
	s_lshl_b32 s38, s2, 1
	v_lshl_add_u64 v[188:189], v[188:189], 0, s[38:39]
	v_lshl_add_u64 v[184:185], v[188:189], 0, s[16:17]
	v_mov_b32_e32 v143, v64
	v_mov_b32_e32 v145, v64
	v_lshl_add_u64 v[188:189], v[184:185], 0, v[142:143]
	global_load_dwordx4 v[0:3], v[188:189], off
	global_load_dwordx4 v[4:7], v[188:189], off offset:64
	global_load_dwordx4 v[8:11], v[188:189], off offset:128
	global_load_dwordx4 v[12:15], v[188:189], off offset:192
	global_load_dwordx4 v[16:19], v[188:189], off offset:256
	global_load_dwordx4 v[20:23], v[188:189], off offset:320
	global_load_dwordx4 v[24:27], v[188:189], off offset:384
	global_load_dwordx4 v[28:31], v[188:189], off offset:448
	v_lshl_add_u64 v[184:185], v[184:185], 0, v[144:145]
	s_lshl_b32 s98, s2, 9
	s_mov_b32 s99, 0
	v_lshl_add_u64 v[180:181], v[66:67], 0, s[98:99]
	v_lshl_add_u64 v[182:183], v[140:141], 0, s[98:99]
	s_lshl_b32 s7, s89, 10
	s_sub_u32 s98, s7, 0x1000
	s_subb_u32 s99, 0, 0
	v_lshl_add_u64 v[180:181], v[180:181], 0, s[98:99]
	v_lshl_add_u64 v[182:183], v[182:183], 0, s[98:99]
	v_lshlrev_b32_e32 v178, 4, v204
	v_add_u32_e32 v179, 0x10000, v178
	s_mov_b64 s[98:99], 0x2000
	s_add_i32 m0, s7, 0
	s_nop 0
	global_load_lds_dwordx4 v[180:181], off
	v_lshl_add_u64 v[180:181], v[180:181], 0, s[98:99]
	s_add_i32 m0, s7, 8192
	s_nop 0
	global_load_lds_dwordx4 v[180:181], off
	v_lshl_add_u64 v[180:181], v[180:181], 0, s[98:99]
	s_add_i32 m0, s7, 16384
	s_nop 0
	global_load_lds_dwordx4 v[180:181], off
	v_lshl_add_u64 v[180:181], v[180:181], 0, s[98:99]
	s_add_i32 m0, s7, 24576
	s_nop 0
	global_load_lds_dwordx4 v[180:181], off
	v_lshl_add_u64 v[180:181], v[180:181], 0, s[98:99]
	s_add_i32 m0, s7, 32768
	s_nop 0
	global_load_lds_dwordx4 v[180:181], off
	v_lshl_add_u64 v[180:181], v[180:181], 0, s[98:99]
	s_add_i32 m0, s7, 40960
	s_nop 0
	global_load_lds_dwordx4 v[180:181], off
	v_lshl_add_u64 v[180:181], v[180:181], 0, s[98:99]
	s_add_i32 m0, s7, 49152
	s_nop 0
	global_load_lds_dwordx4 v[180:181], off
	v_lshl_add_u64 v[180:181], v[180:181], 0, s[98:99]
	s_add_i32 m0, s7, 57344
	s_nop 0
	global_load_lds_dwordx4 v[180:181], off
	v_lshl_add_u64 v[180:181], v[180:181], 0, s[98:99]
	s_add_i32 m0, s7, 65536
	s_nop 0
	global_load_lds_dwordx4 v[180:181], off
	v_lshl_add_u64 v[180:181], v[180:181], 0, s[98:99]
	s_add_i32 m0, s7, 73728
	s_nop 0
	global_load_lds_dwordx4 v[180:181], off
	v_lshl_add_u64 v[180:181], v[180:181], 0, s[98:99]
	s_add_i32 m0, s7, 81920
	s_nop 0
	global_load_lds_dwordx4 v[180:181], off
	v_lshl_add_u64 v[180:181], v[180:181], 0, s[98:99]
	s_add_i32 m0, s7, 90112
	s_nop 0
	global_load_lds_dwordx4 v[180:181], off
	v_lshl_add_u64 v[180:181], v[180:181], 0, s[98:99]
	s_add_i32 m0, s7, 98304
	s_nop 0
	global_load_lds_dwordx4 v[180:181], off
	v_lshl_add_u64 v[180:181], v[180:181], 0, s[98:99]
	s_add_i32 m0, s7, 106496
	s_nop 0
	global_load_lds_dwordx4 v[180:181], off
	v_lshl_add_u64 v[180:181], v[180:181], 0, s[98:99]
	s_waitcnt vmcnt(12)
	s_barrier
	s_add_i32 m0, s7, 114688
	s_nop 0
	global_load_lds_dwordx4 v[180:181], off
	v_lshl_add_u64 v[180:181], v[180:181], 0, s[98:99]
	s_add_i32 m0, s7, 122880
	s_nop 0
	global_load_lds_dwordx4 v[180:181], off
	v_lshl_add_u64 v[180:181], v[180:181], 0, s[98:99]
	ds_read_b128 v[104:107], v178 offset:0
	ds_read_b128 v[146:149], v178 offset:8192
	ds_read_b128 v[108:111], v178 offset:1024
	ds_read_b128 v[150:153], v178 offset:9216
	ds_read_b128 v[112:115], v178 offset:2048
	ds_read_b128 v[154:157], v178 offset:10240
	ds_read_b128 v[116:119], v178 offset:3072
	ds_read_b128 v[158:161], v178 offset:11264
	ds_read_b128 v[120:123], v178 offset:4096
	ds_read_b128 v[162:165], v178 offset:12288
	ds_read_b128 v[124:127], v178 offset:5120
	ds_read_b128 v[166:169], v178 offset:13312
	ds_read_b128 v[128:131], v178 offset:6144
	ds_read_b128 v[170:173], v178 offset:14336
	ds_read_b128 v[132:135], v178 offset:7168
	ds_read_b128 v[174:177], v178 offset:15360
	s_waitcnt lgkmcnt(14)
	v_mfma_f32_16x16x32_bf16 v[32:35], v[104:107], v[0:3], 0
	v_mfma_f32_16x16x32_bf16 v[36:39], v[146:149], v[0:3], 0
	s_waitcnt lgkmcnt(12)
	v_mfma_f32_16x16x32_bf16 v[32:35], v[108:111], v[4:7], v[32:35]
	v_mfma_f32_16x16x32_bf16 v[36:39], v[150:153], v[4:7], v[36:39]
	s_waitcnt lgkmcnt(10)
	v_mfma_f32_16x16x32_bf16 v[32:35], v[112:115], v[8:11], v[32:35]
	v_mfma_f32_16x16x32_bf16 v[36:39], v[154:157], v[8:11], v[36:39]
	s_waitcnt lgkmcnt(8)
	v_mfma_f32_16x16x32_bf16 v[32:35], v[116:119], v[12:15], v[32:35]
	v_mfma_f32_16x16x32_bf16 v[36:39], v[158:161], v[12:15], v[36:39]
	s_waitcnt lgkmcnt(6)
	v_mfma_f32_16x16x32_bf16 v[32:35], v[120:123], v[16:19], v[32:35]
	v_mfma_f32_16x16x32_bf16 v[36:39], v[162:165], v[16:19], v[36:39]
	s_waitcnt lgkmcnt(4)
	v_mfma_f32_16x16x32_bf16 v[32:35], v[124:127], v[20:23], v[32:35]
	v_mfma_f32_16x16x32_bf16 v[36:39], v[166:169], v[20:23], v[36:39]
	s_waitcnt lgkmcnt(2)
	v_mfma_f32_16x16x32_bf16 v[32:35], v[128:131], v[24:27], v[32:35]
	v_mfma_f32_16x16x32_bf16 v[36:39], v[170:173], v[24:27], v[36:39]
	s_waitcnt lgkmcnt(0)
	v_mfma_f32_16x16x32_bf16 v[32:35], v[132:135], v[28:31], v[32:35]
	v_mfma_f32_16x16x32_bf16 v[36:39], v[174:177], v[28:31], v[36:39]
	s_waitcnt vmcnt(12)
	s_barrier
; __device__ __forceinline__ f32x4 mfma16(bf16x8 a, bf16x8 b, f32x4 c) { return __builtin_amdgcn_mfma_f32_16x16x32_bf16(a, b, c, 0, 0, 0); }
; __device__ __forceinline__ void mem_task(bf16_t* zb, const bf16_t* kvm_b, const bf16_t* vmt_b, int hm, int t0, int lane, bool do_store) {
;     ...
;     for (int kt = 0; kt < 16; ++kt) {
;         if (kt + 2 < 16) { const bf16_t* kp = kbase + (size_t)(((kt + 2) >> 1) * 32 + 4 * ((kt + 2) & 1)) * 2048;
; #pragma unroll
;             for (int kk = 0; kk < 8; ++kk) kfr[(kt + 2) % 3][kk] = *(const bf16x8*)(kp + kk * 32); }
;         f32x4 acc = zero4;
;         __builtin_amdgcn_s_setprio(1);
; #pragma unroll
;         for (int kk = 0; kk < 8; ++kk) acc = mfma16(kfr[kt % 3][kk], qf[kk], acc);
;         __builtin_amdgcn_s_setprio(0);
;         s[kt] = acc; }
	s_add_i32 m0, s7, 0
	s_nop 0
	global_load_lds_dwordx4 v[182:183], off
	v_lshl_add_u64 v[182:183], v[182:183], 0, s[98:99]
	s_add_i32 m0, s7, 8192
	s_nop 0
	global_load_lds_dwordx4 v[182:183], off
	v_lshl_add_u64 v[182:183], v[182:183], 0, s[98:99]
	ds_read_b128 v[104:107], v178 offset:16384
	ds_read_b128 v[146:149], v178 offset:24576
	ds_read_b128 v[108:111], v178 offset:17408
	ds_read_b128 v[150:153], v178 offset:25600
	ds_read_b128 v[112:115], v178 offset:18432
	ds_read_b128 v[154:157], v178 offset:26624
	ds_read_b128 v[116:119], v178 offset:19456
	ds_read_b128 v[158:161], v178 offset:27648
	ds_read_b128 v[120:123], v178 offset:20480
	ds_read_b128 v[162:165], v178 offset:28672
	ds_read_b128 v[124:127], v178 offset:21504
	ds_read_b128 v[166:169], v178 offset:29696
	ds_read_b128 v[128:131], v178 offset:22528
	ds_read_b128 v[170:173], v178 offset:30720
	ds_read_b128 v[132:135], v178 offset:23552
	ds_read_b128 v[174:177], v178 offset:31744
	s_waitcnt lgkmcnt(14)
	v_mfma_f32_16x16x32_bf16 v[40:43], v[104:107], v[0:3], 0
	v_mfma_f32_16x16x32_bf16 v[44:47], v[146:149], v[0:3], 0
	s_waitcnt lgkmcnt(12)
	v_mfma_f32_16x16x32_bf16 v[40:43], v[108:111], v[4:7], v[40:43]
	v_mfma_f32_16x16x32_bf16 v[44:47], v[150:153], v[4:7], v[44:47]
	s_waitcnt lgkmcnt(10)
	v_mfma_f32_16x16x32_bf16 v[40:43], v[112:115], v[8:11], v[40:43]
	v_mfma_f32_16x16x32_bf16 v[44:47], v[154:157], v[8:11], v[44:47]
	s_waitcnt lgkmcnt(8)
	v_mfma_f32_16x16x32_bf16 v[40:43], v[116:119], v[12:15], v[40:43]
	v_mfma_f32_16x16x32_bf16 v[44:47], v[158:161], v[12:15], v[44:47]
	s_waitcnt lgkmcnt(6)
	v_mfma_f32_16x16x32_bf16 v[40:43], v[120:123], v[16:19], v[40:43]
	v_mfma_f32_16x16x32_bf16 v[44:47], v[162:165], v[16:19], v[44:47]
	s_waitcnt lgkmcnt(4)
	v_mfma_f32_16x16x32_bf16 v[40:43], v[124:127], v[20:23], v[40:43]
	v_mfma_f32_16x16x32_bf16 v[44:47], v[166:169], v[20:23], v[44:47]
	s_waitcnt lgkmcnt(2)
	v_mfma_f32_16x16x32_bf16 v[40:43], v[128:131], v[24:27], v[40:43]
	v_mfma_f32_16x16x32_bf16 v[44:47], v[170:173], v[24:27], v[44:47]
	s_waitcnt lgkmcnt(0)
	v_mfma_f32_16x16x32_bf16 v[40:43], v[132:135], v[28:31], v[40:43]
	v_mfma_f32_16x16x32_bf16 v[44:47], v[174:177], v[28:31], v[44:47]
	s_waitcnt vmcnt(12)
	s_barrier
	s_add_i32 m0, s7, 16384
	s_nop 0
	global_load_lds_dwordx4 v[182:183], off
	v_lshl_add_u64 v[182:183], v[182:183], 0, s[98:99]
	s_add_i32 m0, s7, 24576
	s_nop 0
	global_load_lds_dwordx4 v[182:183], off
	v_lshl_add_u64 v[182:183], v[182:183], 0, s[98:99]
	ds_read_b128 v[104:107], v178 offset:32768
	ds_read_b128 v[146:149], v178 offset:40960
	ds_read_b128 v[108:111], v178 offset:33792
	ds_read_b128 v[150:153], v178 offset:41984
	ds_read_b128 v[112:115], v178 offset:34816
	ds_read_b128 v[154:157], v178 offset:43008
	ds_read_b128 v[116:119], v178 offset:35840
	ds_read_b128 v[158:161], v178 offset:44032
	ds_read_b128 v[120:123], v178 offset:36864
	ds_read_b128 v[162:165], v178 offset:45056
	ds_read_b128 v[124:127], v178 offset:37888
	ds_read_b128 v[166:169], v178 offset:46080
	ds_read_b128 v[128:131], v178 offset:38912
	ds_read_b128 v[170:173], v178 offset:47104
	ds_read_b128 v[132:135], v178 offset:39936
	ds_read_b128 v[174:177], v178 offset:48128
	s_waitcnt lgkmcnt(14)
	v_mfma_f32_16x16x32_bf16 v[48:51], v[104:107], v[0:3], 0
	v_mfma_f32_16x16x32_bf16 v[52:55], v[146:149], v[0:3], 0
	s_waitcnt lgkmcnt(12)
	v_mfma_f32_16x16x32_bf16 v[48:51], v[108:111], v[4:7], v[48:51]
	v_mfma_f32_16x16x32_bf16 v[52:55], v[150:153], v[4:7], v[52:55]
	s_waitcnt lgkmcnt(10)
	v_mfma_f32_16x16x32_bf16 v[48:51], v[112:115], v[8:11], v[48:51]
	v_mfma_f32_16x16x32_bf16 v[52:55], v[154:157], v[8:11], v[52:55]
	s_waitcnt lgkmcnt(8)
	v_mfma_f32_16x16x32_bf16 v[48:51], v[116:119], v[12:15], v[48:51]
	v_mfma_f32_16x16x32_bf16 v[52:55], v[158:161], v[12:15], v[52:55]
	s_waitcnt lgkmcnt(6)
	v_mfma_f32_16x16x32_bf16 v[48:51], v[120:123], v[16:19], v[48:51]
	v_mfma_f32_16x16x32_bf16 v[52:55], v[162:165], v[16:19], v[52:55]
	s_waitcnt lgkmcnt(4)
	v_mfma_f32_16x16x32_bf16 v[48:51], v[124:127], v[20:23], v[48:51]
	v_mfma_f32_16x16x32_bf16 v[52:55], v[166:169], v[20:23], v[52:55]
	s_waitcnt lgkmcnt(2)
	v_mfma_f32_16x16x32_bf16 v[48:51], v[128:131], v[24:27], v[48:51]
	v_mfma_f32_16x16x32_bf16 v[52:55], v[170:173], v[24:27], v[52:55]
	s_waitcnt lgkmcnt(0)
	v_mfma_f32_16x16x32_bf16 v[48:51], v[132:135], v[28:31], v[48:51]
	v_mfma_f32_16x16x32_bf16 v[52:55], v[174:177], v[28:31], v[52:55]
	s_waitcnt vmcnt(12)
	s_barrier
	s_add_i32 m0, s7, 32768
	s_nop 0
	global_load_lds_dwordx4 v[182:183], off
	v_lshl_add_u64 v[182:183], v[182:183], 0, s[98:99]
	s_add_i32 m0, s7, 40960
	s_nop 0
	global_load_lds_dwordx4 v[182:183], off
	v_lshl_add_u64 v[182:183], v[182:183], 0, s[98:99]
	ds_read_b128 v[104:107], v178 offset:49152
	ds_read_b128 v[146:149], v178 offset:57344
	ds_read_b128 v[108:111], v178 offset:50176
	ds_read_b128 v[150:153], v178 offset:58368
	ds_read_b128 v[112:115], v178 offset:51200
	ds_read_b128 v[154:157], v178 offset:59392
	ds_read_b128 v[116:119], v178 offset:52224
	ds_read_b128 v[158:161], v178 offset:60416
	ds_read_b128 v[120:123], v178 offset:53248
	ds_read_b128 v[162:165], v178 offset:61440
	ds_read_b128 v[124:127], v178 offset:54272
	ds_read_b128 v[166:169], v178 offset:62464
	ds_read_b128 v[128:131], v178 offset:55296
	ds_read_b128 v[170:173], v178 offset:63488
	ds_read_b128 v[132:135], v178 offset:56320
	ds_read_b128 v[174:177], v178 offset:64512
	s_waitcnt lgkmcnt(14)
	v_mfma_f32_16x16x32_bf16 v[56:59], v[104:107], v[0:3], 0
	v_mfma_f32_16x16x32_bf16 v[60:63], v[146:149], v[0:3], 0
	s_waitcnt lgkmcnt(12)
	v_mfma_f32_16x16x32_bf16 v[56:59], v[108:111], v[4:7], v[56:59]
	v_mfma_f32_16x16x32_bf16 v[60:63], v[150:153], v[4:7], v[60:63]
	s_waitcnt lgkmcnt(10)
	v_mfma_f32_16x16x32_bf16 v[56:59], v[112:115], v[8:11], v[56:59]
	v_mfma_f32_16x16x32_bf16 v[60:63], v[154:157], v[8:11], v[60:63]
	s_waitcnt lgkmcnt(8)
	v_mfma_f32_16x16x32_bf16 v[56:59], v[116:119], v[12:15], v[56:59]
	v_mfma_f32_16x16x32_bf16 v[60:63], v[158:161], v[12:15], v[60:63]
	s_waitcnt lgkmcnt(6)
	v_mfma_f32_16x16x32_bf16 v[56:59], v[120:123], v[16:19], v[56:59]
	v_mfma_f32_16x16x32_bf16 v[60:63], v[162:165], v[16:19], v[60:63]
	s_waitcnt lgkmcnt(4)
	v_mfma_f32_16x16x32_bf16 v[56:59], v[124:127], v[20:23], v[56:59]
	v_mfma_f32_16x16x32_bf16 v[60:63], v[166:169], v[20:23], v[60:63]
	s_waitcnt lgkmcnt(2)
	v_mfma_f32_16x16x32_bf16 v[56:59], v[128:131], v[24:27], v[56:59]
	v_mfma_f32_16x16x32_bf16 v[60:63], v[170:173], v[24:27], v[60:63]
	s_waitcnt lgkmcnt(0)
	v_mfma_f32_16x16x32_bf16 v[56:59], v[132:135], v[28:31], v[56:59]
	v_mfma_f32_16x16x32_bf16 v[60:63], v[174:177], v[28:31], v[60:63]
	s_waitcnt vmcnt(12)
	s_barrier
; __device__ __forceinline__ f32x4 mfma16(bf16x8 a, bf16x8 b, f32x4 c) { return __builtin_amdgcn_mfma_f32_16x16x32_bf16(a, b, c, 0, 0, 0); }
; __device__ __forceinline__ void mem_task(bf16_t* zb, const bf16_t* kvm_b, const bf16_t* vmt_b, int hm, int t0, int lane, bool do_store) {
;     ...
;     for (int kt = 0; kt < 16; ++kt) {
;         if (kt + 2 < 16) { const bf16_t* kp = kbase + (size_t)(((kt + 2) >> 1) * 32 + 4 * ((kt + 2) & 1)) * 2048;
; #pragma unroll
;             for (int kk = 0; kk < 8; ++kk) kfr[(kt + 2) % 3][kk] = *(const bf16x8*)(kp + kk * 32); }
;         f32x4 acc = zero4;
;         __builtin_amdgcn_s_setprio(1);
; #pragma unroll
;         for (int kk = 0; kk < 8; ++kk) acc = mfma16(kfr[kt % 3][kk], qf[kk], acc);
;         __builtin_amdgcn_s_setprio(0);
;         s[kt] = acc; }
	s_add_i32 m0, s7, 49152
	s_nop 0
	global_load_lds_dwordx4 v[182:183], off
	v_lshl_add_u64 v[182:183], v[182:183], 0, s[98:99]
	s_add_i32 m0, s7, 57344
	s_nop 0
	global_load_lds_dwordx4 v[182:183], off
	v_lshl_add_u64 v[182:183], v[182:183], 0, s[98:99]
	ds_read_b128 v[104:107], v179 offset:0
	ds_read_b128 v[146:149], v179 offset:8192
	ds_read_b128 v[108:111], v179 offset:1024
	ds_read_b128 v[150:153], v179 offset:9216
	ds_read_b128 v[112:115], v179 offset:2048
	ds_read_b128 v[154:157], v179 offset:10240
	ds_read_b128 v[116:119], v179 offset:3072
	ds_read_b128 v[158:161], v179 offset:11264
	ds_read_b128 v[120:123], v179 offset:4096
	ds_read_b128 v[162:165], v179 offset:12288
	ds_read_b128 v[124:127], v179 offset:5120
	ds_read_b128 v[166:169], v179 offset:13312
	ds_read_b128 v[128:131], v179 offset:6144
	ds_read_b128 v[170:173], v179 offset:14336
	ds_read_b128 v[132:135], v179 offset:7168
	ds_read_b128 v[174:177], v179 offset:15360
	s_waitcnt lgkmcnt(14)
	v_mfma_f32_16x16x32_bf16 v[72:75], v[104:107], v[0:3], 0
	v_mfma_f32_16x16x32_bf16 v[76:79], v[146:149], v[0:3], 0
	s_waitcnt lgkmcnt(12)
	v_mfma_f32_16x16x32_bf16 v[72:75], v[108:111], v[4:7], v[72:75]
	v_mfma_f32_16x16x32_bf16 v[76:79], v[150:153], v[4:7], v[76:79]
	s_waitcnt lgkmcnt(10)
	v_mfma_f32_16x16x32_bf16 v[72:75], v[112:115], v[8:11], v[72:75]
	v_mfma_f32_16x16x32_bf16 v[76:79], v[154:157], v[8:11], v[76:79]
	s_waitcnt lgkmcnt(8)
	v_mfma_f32_16x16x32_bf16 v[72:75], v[116:119], v[12:15], v[72:75]
	v_mfma_f32_16x16x32_bf16 v[76:79], v[158:161], v[12:15], v[76:79]
	s_waitcnt lgkmcnt(6)
	v_mfma_f32_16x16x32_bf16 v[72:75], v[120:123], v[16:19], v[72:75]
	v_mfma_f32_16x16x32_bf16 v[76:79], v[162:165], v[16:19], v[76:79]
	s_waitcnt lgkmcnt(4)
	v_mfma_f32_16x16x32_bf16 v[72:75], v[124:127], v[20:23], v[72:75]
	v_mfma_f32_16x16x32_bf16 v[76:79], v[166:169], v[20:23], v[76:79]
	s_waitcnt lgkmcnt(2)
	v_mfma_f32_16x16x32_bf16 v[72:75], v[128:131], v[24:27], v[72:75]
	v_mfma_f32_16x16x32_bf16 v[76:79], v[170:173], v[24:27], v[76:79]
	s_waitcnt lgkmcnt(0)
	v_mfma_f32_16x16x32_bf16 v[72:75], v[132:135], v[28:31], v[72:75]
	v_mfma_f32_16x16x32_bf16 v[76:79], v[174:177], v[28:31], v[76:79]
	s_waitcnt vmcnt(12)
	s_barrier
	s_add_i32 m0, s7, 65536
	s_nop 0
	global_load_lds_dwordx4 v[182:183], off
	v_lshl_add_u64 v[182:183], v[182:183], 0, s[98:99]
	s_add_i32 m0, s7, 73728
	s_nop 0
	global_load_lds_dwordx4 v[182:183], off
	v_lshl_add_u64 v[182:183], v[182:183], 0, s[98:99]
	ds_read_b128 v[104:107], v179 offset:16384
	ds_read_b128 v[146:149], v179 offset:24576
	ds_read_b128 v[108:111], v179 offset:17408
	ds_read_b128 v[150:153], v179 offset:25600
	ds_read_b128 v[112:115], v179 offset:18432
	ds_read_b128 v[154:157], v179 offset:26624
	ds_read_b128 v[116:119], v179 offset:19456
	ds_read_b128 v[158:161], v179 offset:27648
	ds_read_b128 v[120:123], v179 offset:20480
	ds_read_b128 v[162:165], v179 offset:28672
	ds_read_b128 v[124:127], v179 offset:21504
	ds_read_b128 v[166:169], v179 offset:29696
	ds_read_b128 v[128:131], v179 offset:22528
	ds_read_b128 v[170:173], v179 offset:30720
	ds_read_b128 v[132:135], v179 offset:23552
	ds_read_b128 v[174:177], v179 offset:31744
	s_waitcnt lgkmcnt(14)
	v_mfma_f32_16x16x32_bf16 v[80:83], v[104:107], v[0:3], 0
	v_mfma_f32_16x16x32_bf16 v[84:87], v[146:149], v[0:3], 0
	s_waitcnt lgkmcnt(12)
	v_mfma_f32_16x16x32_bf16 v[80:83], v[108:111], v[4:7], v[80:83]
	v_mfma_f32_16x16x32_bf16 v[84:87], v[150:153], v[4:7], v[84:87]
	s_waitcnt lgkmcnt(10)
	v_mfma_f32_16x16x32_bf16 v[80:83], v[112:115], v[8:11], v[80:83]
	v_mfma_f32_16x16x32_bf16 v[84:87], v[154:157], v[8:11], v[84:87]
	s_waitcnt lgkmcnt(8)
	v_mfma_f32_16x16x32_bf16 v[80:83], v[116:119], v[12:15], v[80:83]
	v_mfma_f32_16x16x32_bf16 v[84:87], v[158:161], v[12:15], v[84:87]
	s_waitcnt lgkmcnt(6)
	v_mfma_f32_16x16x32_bf16 v[80:83], v[120:123], v[16:19], v[80:83]
	v_mfma_f32_16x16x32_bf16 v[84:87], v[162:165], v[16:19], v[84:87]
	s_waitcnt lgkmcnt(4)
	v_mfma_f32_16x16x32_bf16 v[80:83], v[124:127], v[20:23], v[80:83]
	v_mfma_f32_16x16x32_bf16 v[84:87], v[166:169], v[20:23], v[84:87]
	s_waitcnt lgkmcnt(2)
	v_mfma_f32_16x16x32_bf16 v[80:83], v[128:131], v[24:27], v[80:83]
	v_mfma_f32_16x16x32_bf16 v[84:87], v[170:173], v[24:27], v[84:87]
	s_waitcnt lgkmcnt(0)
	v_mfma_f32_16x16x32_bf16 v[80:83], v[132:135], v[28:31], v[80:83]
	v_mfma_f32_16x16x32_bf16 v[84:87], v[174:177], v[28:31], v[84:87]
	s_waitcnt vmcnt(12)
	s_barrier
	s_add_i32 m0, s7, 81920
	s_nop 0
	global_load_lds_dwordx4 v[182:183], off
	v_lshl_add_u64 v[182:183], v[182:183], 0, s[98:99]
	s_add_i32 m0, s7, 90112
	s_nop 0
	global_load_lds_dwordx4 v[182:183], off
	v_lshl_add_u64 v[182:183], v[182:183], 0, s[98:99]
	ds_read_b128 v[104:107], v179 offset:32768
	ds_read_b128 v[146:149], v179 offset:40960
	ds_read_b128 v[108:111], v179 offset:33792
	ds_read_b128 v[150:153], v179 offset:41984
	ds_read_b128 v[112:115], v179 offset:34816
	ds_read_b128 v[154:157], v179 offset:43008
	ds_read_b128 v[116:119], v179 offset:35840
	ds_read_b128 v[158:161], v179 offset:44032
	ds_read_b128 v[120:123], v179 offset:36864
	ds_read_b128 v[162:165], v179 offset:45056
	ds_read_b128 v[124:127], v179 offset:37888
	ds_read_b128 v[166:169], v179 offset:46080
	ds_read_b128 v[128:131], v179 offset:38912
	ds_read_b128 v[170:173], v179 offset:47104
	ds_read_b128 v[132:135], v179 offset:39936
	ds_read_b128 v[174:177], v179 offset:48128
	s_waitcnt lgkmcnt(14)
	v_mfma_f32_16x16x32_bf16 v[88:91], v[104:107], v[0:3], 0
	v_mfma_f32_16x16x32_bf16 v[92:95], v[146:149], v[0:3], 0
	s_waitcnt lgkmcnt(12)
	v_mfma_f32_16x16x32_bf16 v[88:91], v[108:111], v[4:7], v[88:91]
	v_mfma_f32_16x16x32_bf16 v[92:95], v[150:153], v[4:7], v[92:95]
	s_waitcnt lgkmcnt(10)
	v_mfma_f32_16x16x32_bf16 v[88:91], v[112:115], v[8:11], v[88:91]
	v_mfma_f32_16x16x32_bf16 v[92:95], v[154:157], v[8:11], v[92:95]
	s_waitcnt lgkmcnt(8)
	v_mfma_f32_16x16x32_bf16 v[88:91], v[116:119], v[12:15], v[88:91]
	v_mfma_f32_16x16x32_bf16 v[92:95], v[158:161], v[12:15], v[92:95]
	s_waitcnt lgkmcnt(6)
	v_mfma_f32_16x16x32_bf16 v[88:91], v[120:123], v[16:19], v[88:91]
	v_mfma_f32_16x16x32_bf16 v[92:95], v[162:165], v[16:19], v[92:95]
	s_waitcnt lgkmcnt(4)
	v_mfma_f32_16x16x32_bf16 v[88:91], v[124:127], v[20:23], v[88:91]
	v_mfma_f32_16x16x32_bf16 v[92:95], v[166:169], v[20:23], v[92:95]
	s_waitcnt lgkmcnt(2)
	v_mfma_f32_16x16x32_bf16 v[88:91], v[128:131], v[24:27], v[88:91]
	v_mfma_f32_16x16x32_bf16 v[92:95], v[170:173], v[24:27], v[92:95]
	s_waitcnt lgkmcnt(0)
	v_mfma_f32_16x16x32_bf16 v[88:91], v[132:135], v[28:31], v[88:91]
	v_mfma_f32_16x16x32_bf16 v[92:95], v[174:177], v[28:31], v[92:95]
	s_waitcnt vmcnt(12)
	s_barrier
; __device__ __forceinline__ f32x4 mfma16(bf16x8 a, bf16x8 b, f32x4 c) { return __builtin_amdgcn_mfma_f32_16x16x32_bf16(a, b, c, 0, 0, 0); }
; __device__ __forceinline__ void mem_task(bf16_t* zb, const bf16_t* kvm_b, const bf16_t* vmt_b, int hm, int t0, int lane, bool do_store) {
;     ...
;     for (int kt = 0; kt < 16; ++kt) {
;         if (kt + 2 < 16) { const bf16_t* kp = kbase + (size_t)(((kt + 2) >> 1) * 32 + 4 * ((kt + 2) & 1)) * 2048;
; #pragma unroll
;             for (int kk = 0; kk < 8; ++kk) kfr[(kt + 2) % 3][kk] = *(const bf16x8*)(kp + kk * 32); }
;         f32x4 acc = zero4;
;         __builtin_amdgcn_s_setprio(1);
; #pragma unroll
;         for (int kk = 0; kk < 8; ++kk) acc = mfma16(kfr[kt % 3][kk], qf[kk], acc);
;         __builtin_amdgcn_s_setprio(0);
;         s[kt] = acc; }
;     float l = 0.f;
; #pragma unroll
;     for (int kt = 0; kt < 16; ++kt)
; #pragma unroll
;         for (int j = 0; j < 4; ++j) { s[kt][j] = __builtin_amdgcn_exp2f(s[kt][j]); l += s[kt][j]; }
	s_add_i32 m0, s7, 98304
	s_nop 0
	global_load_lds_dwordx4 v[182:183], off
	v_lshl_add_u64 v[182:183], v[182:183], 0, s[98:99]
	s_add_i32 m0, s7, 106496
	s_nop 0
	global_load_lds_dwordx4 v[182:183], off
	v_lshl_add_u64 v[182:183], v[182:183], 0, s[98:99]
	ds_read_b128 v[104:107], v179 offset:49152
	ds_read_b128 v[146:149], v179 offset:57344
	ds_read_b128 v[108:111], v179 offset:50176
	ds_read_b128 v[150:153], v179 offset:58368
	ds_read_b128 v[112:115], v179 offset:51200
	ds_read_b128 v[154:157], v179 offset:59392
	ds_read_b128 v[116:119], v179 offset:52224
	ds_read_b128 v[158:161], v179 offset:60416
	ds_read_b128 v[120:123], v179 offset:53248
	ds_read_b128 v[162:165], v179 offset:61440
	ds_read_b128 v[124:127], v179 offset:54272
	ds_read_b128 v[166:169], v179 offset:62464
	ds_read_b128 v[128:131], v179 offset:55296
	ds_read_b128 v[170:173], v179 offset:63488
	ds_read_b128 v[132:135], v179 offset:56320
	ds_read_b128 v[174:177], v179 offset:64512
	s_waitcnt lgkmcnt(14)
	v_mfma_f32_16x16x32_bf16 v[96:99], v[104:107], v[0:3], 0
	v_mfma_f32_16x16x32_bf16 v[100:103], v[146:149], v[0:3], 0
	s_waitcnt lgkmcnt(12)
	v_mfma_f32_16x16x32_bf16 v[96:99], v[108:111], v[4:7], v[96:99]
	v_mfma_f32_16x16x32_bf16 v[100:103], v[150:153], v[4:7], v[100:103]
	s_waitcnt lgkmcnt(10)
	v_mfma_f32_16x16x32_bf16 v[96:99], v[112:115], v[8:11], v[96:99]
	v_mfma_f32_16x16x32_bf16 v[100:103], v[154:157], v[8:11], v[100:103]
	s_waitcnt lgkmcnt(8)
	v_mfma_f32_16x16x32_bf16 v[96:99], v[116:119], v[12:15], v[96:99]
	v_mfma_f32_16x16x32_bf16 v[100:103], v[158:161], v[12:15], v[100:103]
	s_waitcnt lgkmcnt(6)
	v_mfma_f32_16x16x32_bf16 v[96:99], v[120:123], v[16:19], v[96:99]
	v_mfma_f32_16x16x32_bf16 v[100:103], v[162:165], v[16:19], v[100:103]
	s_waitcnt lgkmcnt(4)
	v_mfma_f32_16x16x32_bf16 v[96:99], v[124:127], v[20:23], v[96:99]
	v_mfma_f32_16x16x32_bf16 v[100:103], v[166:169], v[20:23], v[100:103]
	s_waitcnt lgkmcnt(2)
	v_mfma_f32_16x16x32_bf16 v[96:99], v[128:131], v[24:27], v[96:99]
	v_mfma_f32_16x16x32_bf16 v[100:103], v[170:173], v[24:27], v[100:103]
	s_waitcnt lgkmcnt(0)
	v_mfma_f32_16x16x32_bf16 v[96:99], v[132:135], v[28:31], v[96:99]
	v_mfma_f32_16x16x32_bf16 v[100:103], v[174:177], v[28:31], v[100:103]
	s_nop 7
	s_nop 7
	v_exp_f32_e32 v32, v32
	v_exp_f32_e32 v33, v33
	v_add_f32_e32 v190, 0, v32
	v_exp_f32_e32 v34, v34
	v_add_f32_e32 v190, v190, v33
	v_exp_f32_e32 v35, v35
	v_add_f32_e32 v190, v190, v34
	v_exp_f32_e32 v36, v36
	v_add_f32_e32 v190, v190, v35
	v_exp_f32_e32 v37, v37
	v_add_f32_e32 v190, v190, v36
	v_exp_f32_e32 v38, v38
	v_add_f32_e32 v190, v190, v37
	v_exp_f32_e32 v39, v39
	v_add_f32_e32 v190, v190, v38
	v_exp_f32_e32 v40, v40
	v_add_f32_e32 v190, v190, v39
	v_exp_f32_e32 v41, v41
	v_add_f32_e32 v190, v190, v40
	v_exp_f32_e32 v42, v42
	v_add_f32_e32 v190, v190, v41
	v_exp_f32_e32 v43, v43
	v_add_f32_e32 v190, v190, v42
	v_exp_f32_e32 v44, v44
	v_add_f32_e32 v190, v190, v43
	v_exp_f32_e32 v45, v45
	v_add_f32_e32 v190, v190, v44
	v_exp_f32_e32 v46, v46
	v_add_f32_e32 v190, v190, v45
	v_exp_f32_e32 v47, v47
	v_add_f32_e32 v190, v190, v46
	v_exp_f32_e32 v48, v48
	v_add_f32_e32 v190, v190, v47
	v_exp_f32_e32 v49, v49
	v_add_f32_e32 v190, v190, v48
	v_exp_f32_e32 v50, v50
	v_add_f32_e32 v190, v190, v49
	v_exp_f32_e32 v51, v51
	v_add_f32_e32 v190, v190, v50
	v_exp_f32_e32 v52, v52
	v_add_f32_e32 v190, v190, v51
	v_exp_f32_e32 v53, v53
	v_add_f32_e32 v190, v190, v52
	v_exp_f32_e32 v54, v54
	v_add_f32_e32 v190, v190, v53
	v_exp_f32_e32 v55, v55
	v_add_f32_e32 v190, v190, v54
	v_exp_f32_e32 v56, v56
	v_add_f32_e32 v190, v190, v55
	v_exp_f32_e32 v57, v57
	v_add_f32_e32 v190, v190, v56
	v_exp_f32_e32 v58, v58
	v_add_f32_e32 v190, v190, v57
	v_exp_f32_e32 v59, v59
	v_add_f32_e32 v190, v190, v58
	v_exp_f32_e32 v60, v60
	v_add_f32_e32 v190, v190, v59
	v_exp_f32_e32 v61, v61
	v_add_f32_e32 v190, v190, v60
	v_exp_f32_e32 v62, v62
	v_add_f32_e32 v190, v190, v61
	v_exp_f32_e32 v63, v63
	v_add_f32_e32 v190, v190, v62
	v_exp_f32_e32 v72, v72
	v_add_f32_e32 v190, v190, v63
	v_exp_f32_e32 v73, v73
	v_add_f32_e32 v190, v190, v72
	v_exp_f32_e32 v74, v74
	v_add_f32_e32 v190, v190, v73
	v_exp_f32_e32 v75, v75
	v_add_f32_e32 v190, v190, v74
	v_exp_f32_e32 v76, v76
	v_add_f32_e32 v190, v190, v75
	v_exp_f32_e32 v77, v77
	v_add_f32_e32 v190, v190, v76
	v_exp_f32_e32 v78, v78
	v_add_f32_e32 v190, v190, v77
	v_exp_f32_e32 v79, v79
	v_add_f32_e32 v190, v190, v78
	v_exp_f32_e32 v80, v80
	v_add_f32_e32 v190, v190, v79
	v_exp_f32_e32 v81, v81
	v_add_f32_e32 v190, v190, v80
	v_exp_f32_e32 v82, v82
	v_add_f32_e32 v190, v190, v81
	v_exp_f32_e32 v83, v83
	v_add_f32_e32 v190, v190, v82
	v_exp_f32_e32 v84, v84
	v_add_f32_e32 v190, v190, v83
	v_exp_f32_e32 v85, v85
	v_add_f32_e32 v190, v190, v84
	v_exp_f32_e32 v86, v86
	v_add_f32_e32 v190, v190, v85
	v_exp_f32_e32 v87, v87
	v_add_f32_e32 v190, v190, v86
	v_exp_f32_e32 v88, v88
	v_add_f32_e32 v190, v190, v87
	v_exp_f32_e32 v89, v89
	v_add_f32_e32 v190, v190, v88
	v_exp_f32_e32 v90, v90
	v_add_f32_e32 v190, v190, v89
	v_exp_f32_e32 v91, v91
	v_add_f32_e32 v190, v190, v90
	v_exp_f32_e32 v92, v92
	v_add_f32_e32 v190, v190, v91
	v_exp_f32_e32 v93, v93
	v_add_f32_e32 v190, v190, v92
	v_exp_f32_e32 v94, v94
	v_add_f32_e32 v190, v190, v93
	v_exp_f32_e32 v95, v95
	v_add_f32_e32 v190, v190, v94
	v_exp_f32_e32 v96, v96
	v_add_f32_e32 v190, v190, v95
	v_exp_f32_e32 v97, v97
	v_add_f32_e32 v190, v190, v96
	v_exp_f32_e32 v98, v98
	v_add_f32_e32 v190, v190, v97
	v_exp_f32_e32 v99, v99
	v_add_f32_e32 v190, v190, v98
	v_exp_f32_e32 v100, v100
	v_add_f32_e32 v190, v190, v99
	v_exp_f32_e32 v101, v101
	v_add_f32_e32 v190, v190, v100
	v_exp_f32_e32 v102, v102
; __device__ __forceinline__ unsigned cvt_pk_bf16(float lo, float hi) { unsigned r; asm volatile("v_cvt_pk_bf16_f32 %0, %1, %2" : "=v"(r) : "v"(lo), "v"(hi)); return r; }
; __device__ __forceinline__ f32x4 mfma16(bf16x8 a, bf16x8 b, f32x4 c) { return __builtin_amdgcn_mfma_f32_16x16x32_bf16(a, b, c, 0, 0, 0); }
; __device__ __forceinline__ float x16sum(float x) { auto r = __builtin_amdgcn_permlane16_swap(__float_as_uint(x), __float_as_uint(x), false, false); return __uint_as_float(r[0]) + __uint_as_float(r[1]); }
; __device__ __forceinline__ float x32sum(float x) { auto r = __builtin_amdgcn_permlane32_swap(__float_as_uint(x), __float_as_uint(x), false, false); return __uint_as_float(r[0]) + __uint_as_float(r[1]); }
; __device__ __forceinline__ void mem_task(bf16_t* zb, const bf16_t* kvm_b, const bf16_t* vmt_b, int hm, int t0, int lane, bool do_store) {
;     ...
;         for (int j = 0; j < 4; ++j) { s[kt][j] = __builtin_amdgcn_exp2f(s[kt][j]); l += s[kt][j]; }
;     l = x16sum(l); l = x32sum(l);
;     const float il = 1.0f / l;
;     bf16x8 pf[8];
; #pragma unroll
;     for (int kp = 0; kp < 8; ++kp) { u32x4 w; w.x = cvt_pk_bf16(s[2 * kp][0], s[2 * kp][1]); w.y = cvt_pk_bf16(s[2 * kp][2], s[2 * kp][3]); w.z = cvt_pk_bf16(s[2 * kp + 1][0], s[2 * kp + 1][1]); w.w = cvt_pk_bf16(s[2 * kp + 1][2], s[2 * kp + 1][3]); pf[kp] = __builtin_bit_cast(bf16x8, w); }
;     const bf16_t* vbase = vmt_b + (size_t)(hm * 256 + n) * 256 + 8 * fq;
;     bf16x8 vfr[3][8];
; #pragma unroll
;     for (int kp = 0; kp < 8; ++kp) vfr[0][kp] = *(const bf16x8*)(vbase + kp * 32);
;     { const bf16_t* vp = vbase + (size_t)16 * 256;
; #pragma unroll
;       for (int kp = 0; kp < 8; ++kp) vfr[1][kp] = *(const bf16x8*)(vp + kp * 32); }
; #pragma unroll
;     for (int dt = 0; dt < 16; ++dt) {
;         if (dt + 2 < 16) { const bf16_t* vp = vbase + (size_t)((dt + 2) * 16) * 256;
; #pragma unroll
;             for (int kp = 0; kp < 8; ++kp) vfr[(dt + 2) % 3][kp] = *(const bf16x8*)(vp + kp * 32); }
;         f32x4 acc = zero4;
;         __builtin_amdgcn_s_setprio(1);
; #pragma unroll
;         for (int kp = 0; kp < 8; ++kp) acc = mfma16(vfr[dt % 3][kp], pf[kp], acc);
;         __builtin_amdgcn_s_setprio(0);
;         u32x2 w; w.x = cvt_pk_bf16(acc[0] * il, acc[1] * il); w.y = cvt_pk_bf16(acc[2] * il, acc[3] * il); if (do_store || acc[0] == 12345.678f) *(u32x2*)(qp + dt * 16 + 4 * fq) = w; }
	v_add_f32_e32 v190, v190, v101
	v_exp_f32_e32 v103, v103
	v_add_f32_e32 v190, v190, v102
	s_nop 0
	v_add_f32_e32 v190, v190, v103
	v_mov_b32_e32 v186, v190
	s_nop 1
	v_permlane16_swap_b32_e32 v190, v186
	v_add_f32_e32 v190, v190, v186
	v_mov_b32_e32 v186, v190
	s_nop 1
	v_permlane32_swap_b32_e32 v190, v186
	v_add_f32_e32 v190, v190, v186
	v_div_scale_f32 v186, s[12:13], v190, v190, 1.0
	v_rcp_f32_e32 v187, v186
	s_nop 0
	v_fma_f32 v188, -v186, v187, 1.0
	v_fmac_f32_e32 v187, v188, v187
	v_div_scale_f32 v188, vcc, 1.0, v190, 1.0
	v_mul_f32_e32 v189, v188, v187
	v_fma_f32 v136, -v186, v189, v188
	v_fmac_f32_e32 v189, v136, v187
	v_fma_f32 v186, -v186, v189, v188
	s_nop 0
	v_div_fmas_f32 v186, v186, v187, v189
	v_div_fixup_f32 v191, v186, v190, 1.0
	v_cvt_pk_bf16_f32 v32, v32, v33
	v_cvt_pk_bf16_f32 v33, v34, v35
	v_cvt_pk_bf16_f32 v34, v36, v37
	v_cvt_pk_bf16_f32 v35, v38, v39
	v_cvt_pk_bf16_f32 v40, v40, v41
	v_cvt_pk_bf16_f32 v41, v42, v43
	v_cvt_pk_bf16_f32 v42, v44, v45
	v_cvt_pk_bf16_f32 v43, v46, v47
	v_cvt_pk_bf16_f32 v48, v48, v49
	v_cvt_pk_bf16_f32 v49, v50, v51
	v_cvt_pk_bf16_f32 v50, v52, v53
	v_cvt_pk_bf16_f32 v51, v54, v55
	v_cvt_pk_bf16_f32 v56, v56, v57
	v_cvt_pk_bf16_f32 v57, v58, v59
	v_cvt_pk_bf16_f32 v58, v60, v61
	v_cvt_pk_bf16_f32 v59, v62, v63
	v_cvt_pk_bf16_f32 v72, v72, v73
	v_cvt_pk_bf16_f32 v73, v74, v75
	v_cvt_pk_bf16_f32 v74, v76, v77
	v_cvt_pk_bf16_f32 v75, v78, v79
	v_cvt_pk_bf16_f32 v80, v80, v81
	v_cvt_pk_bf16_f32 v81, v82, v83
	v_cvt_pk_bf16_f32 v82, v84, v85
	v_cvt_pk_bf16_f32 v83, v86, v87
	v_cvt_pk_bf16_f32 v88, v88, v89
	v_cvt_pk_bf16_f32 v89, v90, v91
	v_cvt_pk_bf16_f32 v90, v92, v93
	v_cvt_pk_bf16_f32 v91, v94, v95
	v_cvt_pk_bf16_f32 v96, v96, v97
	v_cvt_pk_bf16_f32 v97, v98, v99
	v_cvt_pk_bf16_f32 v98, v100, v101
	v_cvt_pk_bf16_f32 v99, v102, v103
	s_waitcnt vmcnt(12)
	s_barrier
	s_add_i32 m0, s7, 114688
	s_nop 0
	global_load_lds_dwordx4 v[182:183], off
	v_lshl_add_u64 v[182:183], v[182:183], 0, s[98:99]
	s_add_i32 m0, s7, 122880
	s_nop 0
	global_load_lds_dwordx4 v[182:183], off
	v_lshl_add_u64 v[182:183], v[182:183], 0, s[98:99]
	ds_read_b128 v[104:107], v178 offset:0
	ds_read_b128 v[146:149], v178 offset:8192
	ds_read_b128 v[108:111], v178 offset:1024
	ds_read_b128 v[150:153], v178 offset:9216
	ds_read_b128 v[112:115], v178 offset:2048
	ds_read_b128 v[154:157], v178 offset:10240
	ds_read_b128 v[116:119], v178 offset:3072
	ds_read_b128 v[158:161], v178 offset:11264
	ds_read_b128 v[120:123], v178 offset:4096
	ds_read_b128 v[162:165], v178 offset:12288
	ds_read_b128 v[124:127], v178 offset:5120
	ds_read_b128 v[166:169], v178 offset:13312
	ds_read_b128 v[128:131], v178 offset:6144
	ds_read_b128 v[170:173], v178 offset:14336
	ds_read_b128 v[132:135], v178 offset:7168
	ds_read_b128 v[174:177], v178 offset:15360
	s_waitcnt lgkmcnt(14)
	v_mfma_f32_16x16x32_bf16 v[192:195], v[104:107], v[32:35], 0
	v_mfma_f32_16x16x32_bf16 v[196:199], v[146:149], v[32:35], 0
	s_waitcnt lgkmcnt(12)
	v_mfma_f32_16x16x32_bf16 v[192:195], v[108:111], v[40:43], v[192:195]
	v_mfma_f32_16x16x32_bf16 v[196:199], v[150:153], v[40:43], v[196:199]
	s_waitcnt lgkmcnt(10)
	v_mfma_f32_16x16x32_bf16 v[192:195], v[112:115], v[48:51], v[192:195]
	v_mfma_f32_16x16x32_bf16 v[196:199], v[154:157], v[48:51], v[196:199]
	s_waitcnt lgkmcnt(8)
	v_mfma_f32_16x16x32_bf16 v[192:195], v[116:119], v[56:59], v[192:195]
	v_mfma_f32_16x16x32_bf16 v[196:199], v[158:161], v[56:59], v[196:199]
	s_waitcnt lgkmcnt(6)
	v_mfma_f32_16x16x32_bf16 v[192:195], v[120:123], v[72:75], v[192:195]
	v_mfma_f32_16x16x32_bf16 v[196:199], v[162:165], v[72:75], v[196:199]
	s_waitcnt lgkmcnt(4)
	v_mfma_f32_16x16x32_bf16 v[192:195], v[124:127], v[80:83], v[192:195]
	v_mfma_f32_16x16x32_bf16 v[196:199], v[166:169], v[80:83], v[196:199]
	s_waitcnt lgkmcnt(2)
	v_mfma_f32_16x16x32_bf16 v[192:195], v[128:131], v[88:91], v[192:195]
	v_mfma_f32_16x16x32_bf16 v[196:199], v[170:173], v[88:91], v[196:199]
	s_waitcnt lgkmcnt(0)
	v_mfma_f32_16x16x32_bf16 v[192:195], v[132:135], v[96:99], v[192:195]
	v_mfma_f32_16x16x32_bf16 v[196:199], v[174:177], v[96:99], v[196:199]
	s_waitcnt vmcnt(12)
	s_barrier
	ds_read_b128 v[104:107], v178 offset:16384
	ds_read_b128 v[146:149], v178 offset:24576
	ds_read_b128 v[108:111], v178 offset:17408
	ds_read_b128 v[150:153], v178 offset:25600
	ds_read_b128 v[112:115], v178 offset:18432
	ds_read_b128 v[154:157], v178 offset:26624
	ds_read_b128 v[116:119], v178 offset:19456
	ds_read_b128 v[158:161], v178 offset:27648
	ds_read_b128 v[120:123], v178 offset:20480
	ds_read_b128 v[162:165], v178 offset:28672
	ds_read_b128 v[124:127], v178 offset:21504
	ds_read_b128 v[166:169], v178 offset:29696
	ds_read_b128 v[128:131], v178 offset:22528
	ds_read_b128 v[170:173], v178 offset:30720
	ds_read_b128 v[132:135], v178 offset:23552
	ds_read_b128 v[174:177], v178 offset:31744
	s_waitcnt lgkmcnt(14)
	v_mfma_f32_16x16x32_bf16 v[206:209], v[104:107], v[32:35], 0
	v_mfma_f32_16x16x32_bf16 v[210:213], v[146:149], v[32:35], 0
	s_waitcnt lgkmcnt(12)
	v_mfma_f32_16x16x32_bf16 v[206:209], v[108:111], v[40:43], v[206:209]
	v_mfma_f32_16x16x32_bf16 v[210:213], v[150:153], v[40:43], v[210:213]
	s_waitcnt lgkmcnt(10)
	v_mfma_f32_16x16x32_bf16 v[206:209], v[112:115], v[48:51], v[206:209]
	v_mfma_f32_16x16x32_bf16 v[210:213], v[154:157], v[48:51], v[210:213]
	s_waitcnt lgkmcnt(8)
	v_mfma_f32_16x16x32_bf16 v[206:209], v[116:119], v[56:59], v[206:209]
	v_mfma_f32_16x16x32_bf16 v[210:213], v[158:161], v[56:59], v[210:213]
	s_waitcnt lgkmcnt(6)
	v_mfma_f32_16x16x32_bf16 v[206:209], v[120:123], v[72:75], v[206:209]
	v_mfma_f32_16x16x32_bf16 v[210:213], v[162:165], v[72:75], v[210:213]
	s_waitcnt lgkmcnt(4)
	v_mfma_f32_16x16x32_bf16 v[206:209], v[124:127], v[80:83], v[206:209]
	v_mfma_f32_16x16x32_bf16 v[210:213], v[166:169], v[80:83], v[210:213]
	s_waitcnt lgkmcnt(2)
	v_mfma_f32_16x16x32_bf16 v[206:209], v[128:131], v[88:91], v[206:209]
	v_mfma_f32_16x16x32_bf16 v[210:213], v[170:173], v[88:91], v[210:213]
	s_waitcnt lgkmcnt(0)
	v_mfma_f32_16x16x32_bf16 v[206:209], v[132:135], v[96:99], v[206:209]
	v_mfma_f32_16x16x32_bf16 v[210:213], v[174:177], v[96:99], v[210:213]
	v_mul_f32_e32 v192, v191, v192
	v_mul_f32_e32 v193, v191, v193
	v_mul_f32_e32 v194, v191, v194
	v_mul_f32_e32 v195, v191, v195
	v_cvt_pk_bf16_f32 v192, v192, v193
	v_cvt_pk_bf16_f32 v193, v194, v195
	global_store_dwordx2 v[184:185], v[192:193], off
	v_mul_f32_e32 v196, v191, v196
	v_mul_f32_e32 v197, v191, v197
	v_mul_f32_e32 v198, v191, v198
	v_mul_f32_e32 v199, v191, v199
	v_cvt_pk_bf16_f32 v196, v196, v197
	v_cvt_pk_bf16_f32 v197, v198, v199
	global_store_dwordx2 v[184:185], v[196:197], off offset:32
	s_waitcnt vmcnt(12)
	s_barrier
; __device__ __forceinline__ unsigned cvt_pk_bf16(float lo, float hi) { unsigned r; asm volatile("v_cvt_pk_bf16_f32 %0, %1, %2" : "=v"(r) : "v"(lo), "v"(hi)); return r; }
; __device__ __forceinline__ f32x4 mfma16(bf16x8 a, bf16x8 b, f32x4 c) { return __builtin_amdgcn_mfma_f32_16x16x32_bf16(a, b, c, 0, 0, 0); }
; __device__ __forceinline__ void mem_task(bf16_t* zb, const bf16_t* kvm_b, const bf16_t* vmt_b, int hm, int t0, int lane, bool do_store) {
;     ...
;     for (int dt = 0; dt < 16; ++dt) {
;         if (dt + 2 < 16) { const bf16_t* vp = vbase + (size_t)((dt + 2) * 16) * 256;
; #pragma unroll
;             for (int kp = 0; kp < 8; ++kp) vfr[(dt + 2) % 3][kp] = *(const bf16x8*)(vp + kp * 32); }
;         f32x4 acc = zero4;
;         __builtin_amdgcn_s_setprio(1);
; #pragma unroll
;         for (int kp = 0; kp < 8; ++kp) acc = mfma16(vfr[dt % 3][kp], pf[kp], acc);
;         __builtin_amdgcn_s_setprio(0);
;         u32x2 w; w.x = cvt_pk_bf16(acc[0] * il, acc[1] * il); w.y = cvt_pk_bf16(acc[2] * il, acc[3] * il); if (do_store || acc[0] == 12345.678f) *(u32x2*)(qp + dt * 16 + 4 * fq) = w; }
	ds_read_b128 v[104:107], v178 offset:32768
	ds_read_b128 v[146:149], v178 offset:40960
	ds_read_b128 v[108:111], v178 offset:33792
	ds_read_b128 v[150:153], v178 offset:41984
	ds_read_b128 v[112:115], v178 offset:34816
	ds_read_b128 v[154:157], v178 offset:43008
	ds_read_b128 v[116:119], v178 offset:35840
	ds_read_b128 v[158:161], v178 offset:44032
	ds_read_b128 v[120:123], v178 offset:36864
	ds_read_b128 v[162:165], v178 offset:45056
	ds_read_b128 v[124:127], v178 offset:37888
	ds_read_b128 v[166:169], v178 offset:46080
	ds_read_b128 v[128:131], v178 offset:38912
	ds_read_b128 v[170:173], v178 offset:47104
	ds_read_b128 v[132:135], v178 offset:39936
	ds_read_b128 v[174:177], v178 offset:48128
	s_waitcnt lgkmcnt(14)
	v_mfma_f32_16x16x32_bf16 v[192:195], v[104:107], v[32:35], 0
	v_mfma_f32_16x16x32_bf16 v[196:199], v[146:149], v[32:35], 0
	s_waitcnt lgkmcnt(12)
	v_mfma_f32_16x16x32_bf16 v[192:195], v[108:111], v[40:43], v[192:195]
	v_mfma_f32_16x16x32_bf16 v[196:199], v[150:153], v[40:43], v[196:199]
	s_waitcnt lgkmcnt(10)
	v_mfma_f32_16x16x32_bf16 v[192:195], v[112:115], v[48:51], v[192:195]
	v_mfma_f32_16x16x32_bf16 v[196:199], v[154:157], v[48:51], v[196:199]
	s_waitcnt lgkmcnt(8)
	v_mfma_f32_16x16x32_bf16 v[192:195], v[116:119], v[56:59], v[192:195]
	v_mfma_f32_16x16x32_bf16 v[196:199], v[158:161], v[56:59], v[196:199]
	s_waitcnt lgkmcnt(6)
	v_mfma_f32_16x16x32_bf16 v[192:195], v[120:123], v[72:75], v[192:195]
	v_mfma_f32_16x16x32_bf16 v[196:199], v[162:165], v[72:75], v[196:199]
	s_waitcnt lgkmcnt(4)
	v_mfma_f32_16x16x32_bf16 v[192:195], v[124:127], v[80:83], v[192:195]
	v_mfma_f32_16x16x32_bf16 v[196:199], v[166:169], v[80:83], v[196:199]
	s_waitcnt lgkmcnt(2)
	v_mfma_f32_16x16x32_bf16 v[192:195], v[128:131], v[88:91], v[192:195]
	v_mfma_f32_16x16x32_bf16 v[196:199], v[170:173], v[88:91], v[196:199]
	s_waitcnt lgkmcnt(0)
	v_mfma_f32_16x16x32_bf16 v[192:195], v[132:135], v[96:99], v[192:195]
	v_mfma_f32_16x16x32_bf16 v[196:199], v[174:177], v[96:99], v[196:199]
	v_mul_f32_e32 v206, v191, v206
	v_mul_f32_e32 v207, v191, v207
	v_mul_f32_e32 v208, v191, v208
	v_mul_f32_e32 v209, v191, v209
	v_cvt_pk_bf16_f32 v206, v206, v207
	v_cvt_pk_bf16_f32 v207, v208, v209
	global_store_dwordx2 v[184:185], v[206:207], off offset:64
	v_mul_f32_e32 v210, v191, v210
	v_mul_f32_e32 v211, v191, v211
	v_mul_f32_e32 v212, v191, v212
	v_mul_f32_e32 v213, v191, v213
	v_cvt_pk_bf16_f32 v210, v210, v211
	v_cvt_pk_bf16_f32 v211, v212, v213
	global_store_dwordx2 v[184:185], v[210:211], off offset:96
	s_waitcnt vmcnt(12)
	s_barrier
	ds_read_b128 v[104:107], v178 offset:49152
	ds_read_b128 v[146:149], v178 offset:57344
	ds_read_b128 v[108:111], v178 offset:50176
	ds_read_b128 v[150:153], v178 offset:58368
	ds_read_b128 v[112:115], v178 offset:51200
	ds_read_b128 v[154:157], v178 offset:59392
	ds_read_b128 v[116:119], v178 offset:52224
	ds_read_b128 v[158:161], v178 offset:60416
	ds_read_b128 v[120:123], v178 offset:53248
	ds_read_b128 v[162:165], v178 offset:61440
	ds_read_b128 v[124:127], v178 offset:54272
	ds_read_b128 v[166:169], v178 offset:62464
	ds_read_b128 v[128:131], v178 offset:55296
	ds_read_b128 v[170:173], v178 offset:63488
	ds_read_b128 v[132:135], v178 offset:56320
	ds_read_b128 v[174:177], v178 offset:64512
	s_waitcnt lgkmcnt(14)
	v_mfma_f32_16x16x32_bf16 v[206:209], v[104:107], v[32:35], 0
	v_mfma_f32_16x16x32_bf16 v[210:213], v[146:149], v[32:35], 0
	s_waitcnt lgkmcnt(12)
	v_mfma_f32_16x16x32_bf16 v[206:209], v[108:111], v[40:43], v[206:209]
	v_mfma_f32_16x16x32_bf16 v[210:213], v[150:153], v[40:43], v[210:213]
	s_waitcnt lgkmcnt(10)
	v_mfma_f32_16x16x32_bf16 v[206:209], v[112:115], v[48:51], v[206:209]
	v_mfma_f32_16x16x32_bf16 v[210:213], v[154:157], v[48:51], v[210:213]
	s_waitcnt lgkmcnt(8)
	v_mfma_f32_16x16x32_bf16 v[206:209], v[116:119], v[56:59], v[206:209]
	v_mfma_f32_16x16x32_bf16 v[210:213], v[158:161], v[56:59], v[210:213]
	s_waitcnt lgkmcnt(6)
	v_mfma_f32_16x16x32_bf16 v[206:209], v[120:123], v[72:75], v[206:209]
	v_mfma_f32_16x16x32_bf16 v[210:213], v[162:165], v[72:75], v[210:213]
	s_waitcnt lgkmcnt(4)
	v_mfma_f32_16x16x32_bf16 v[206:209], v[124:127], v[80:83], v[206:209]
	v_mfma_f32_16x16x32_bf16 v[210:213], v[166:169], v[80:83], v[210:213]
	s_waitcnt lgkmcnt(2)
	v_mfma_f32_16x16x32_bf16 v[206:209], v[128:131], v[88:91], v[206:209]
	v_mfma_f32_16x16x32_bf16 v[210:213], v[170:173], v[88:91], v[210:213]
	s_waitcnt lgkmcnt(0)
	v_mfma_f32_16x16x32_bf16 v[206:209], v[132:135], v[96:99], v[206:209]
	v_mfma_f32_16x16x32_bf16 v[210:213], v[174:177], v[96:99], v[210:213]
	v_mul_f32_e32 v192, v191, v192
	v_mul_f32_e32 v193, v191, v193
	v_mul_f32_e32 v194, v191, v194
	v_mul_f32_e32 v195, v191, v195
	v_cvt_pk_bf16_f32 v192, v192, v193
	v_cvt_pk_bf16_f32 v193, v194, v195
	global_store_dwordx2 v[184:185], v[192:193], off offset:128
	v_mul_f32_e32 v196, v191, v196
	v_mul_f32_e32 v197, v191, v197
	v_mul_f32_e32 v198, v191, v198
	v_mul_f32_e32 v199, v191, v199
	v_cvt_pk_bf16_f32 v196, v196, v197
	v_cvt_pk_bf16_f32 v197, v198, v199
	global_store_dwordx2 v[184:185], v[196:197], off offset:160
	s_waitcnt vmcnt(12)
	s_barrier
; __device__ __forceinline__ unsigned cvt_pk_bf16(float lo, float hi) { unsigned r; asm volatile("v_cvt_pk_bf16_f32 %0, %1, %2" : "=v"(r) : "v"(lo), "v"(hi)); return r; }
; __device__ __forceinline__ f32x4 mfma16(bf16x8 a, bf16x8 b, f32x4 c) { return __builtin_amdgcn_mfma_f32_16x16x32_bf16(a, b, c, 0, 0, 0); }
; __device__ __forceinline__ void mem_task(bf16_t* zb, const bf16_t* kvm_b, const bf16_t* vmt_b, int hm, int t0, int lane, bool do_store) {
;     ...
;     for (int dt = 0; dt < 16; ++dt) {
;         if (dt + 2 < 16) { const bf16_t* vp = vbase + (size_t)((dt + 2) * 16) * 256;
; #pragma unroll
;             for (int kp = 0; kp < 8; ++kp) vfr[(dt + 2) % 3][kp] = *(const bf16x8*)(vp + kp * 32); }
;         f32x4 acc = zero4;
;         __builtin_amdgcn_s_setprio(1);
; #pragma unroll
;         for (int kp = 0; kp < 8; ++kp) acc = mfma16(vfr[dt % 3][kp], pf[kp], acc);
;         __builtin_amdgcn_s_setprio(0);
;         u32x2 w; w.x = cvt_pk_bf16(acc[0] * il, acc[1] * il); w.y = cvt_pk_bf16(acc[2] * il, acc[3] * il); if (do_store || acc[0] == 12345.678f) *(u32x2*)(qp + dt * 16 + 4 * fq) = w; }
	ds_read_b128 v[104:107], v179 offset:0
	ds_read_b128 v[146:149], v179 offset:8192
	ds_read_b128 v[108:111], v179 offset:1024
	ds_read_b128 v[150:153], v179 offset:9216
	ds_read_b128 v[112:115], v179 offset:2048
	ds_read_b128 v[154:157], v179 offset:10240
	ds_read_b128 v[116:119], v179 offset:3072
	ds_read_b128 v[158:161], v179 offset:11264
	ds_read_b128 v[120:123], v179 offset:4096
	ds_read_b128 v[162:165], v179 offset:12288
	ds_read_b128 v[124:127], v179 offset:5120
	ds_read_b128 v[166:169], v179 offset:13312
	ds_read_b128 v[128:131], v179 offset:6144
	ds_read_b128 v[170:173], v179 offset:14336
	ds_read_b128 v[132:135], v179 offset:7168
	ds_read_b128 v[174:177], v179 offset:15360
	s_waitcnt lgkmcnt(14)
	v_mfma_f32_16x16x32_bf16 v[192:195], v[104:107], v[32:35], 0
	v_mfma_f32_16x16x32_bf16 v[196:199], v[146:149], v[32:35], 0
	s_waitcnt lgkmcnt(12)
	v_mfma_f32_16x16x32_bf16 v[192:195], v[108:111], v[40:43], v[192:195]
	v_mfma_f32_16x16x32_bf16 v[196:199], v[150:153], v[40:43], v[196:199]
	s_waitcnt lgkmcnt(10)
	v_mfma_f32_16x16x32_bf16 v[192:195], v[112:115], v[48:51], v[192:195]
	v_mfma_f32_16x16x32_bf16 v[196:199], v[154:157], v[48:51], v[196:199]
	s_waitcnt lgkmcnt(8)
	v_mfma_f32_16x16x32_bf16 v[192:195], v[116:119], v[56:59], v[192:195]
	v_mfma_f32_16x16x32_bf16 v[196:199], v[158:161], v[56:59], v[196:199]
	s_waitcnt lgkmcnt(6)
	v_mfma_f32_16x16x32_bf16 v[192:195], v[120:123], v[72:75], v[192:195]
	v_mfma_f32_16x16x32_bf16 v[196:199], v[162:165], v[72:75], v[196:199]
	s_waitcnt lgkmcnt(4)
	v_mfma_f32_16x16x32_bf16 v[192:195], v[124:127], v[80:83], v[192:195]
	v_mfma_f32_16x16x32_bf16 v[196:199], v[166:169], v[80:83], v[196:199]
	s_waitcnt lgkmcnt(2)
	v_mfma_f32_16x16x32_bf16 v[192:195], v[128:131], v[88:91], v[192:195]
	v_mfma_f32_16x16x32_bf16 v[196:199], v[170:173], v[88:91], v[196:199]
	s_waitcnt lgkmcnt(0)
	v_mfma_f32_16x16x32_bf16 v[192:195], v[132:135], v[96:99], v[192:195]
	v_mfma_f32_16x16x32_bf16 v[196:199], v[174:177], v[96:99], v[196:199]
	v_mul_f32_e32 v206, v191, v206
	v_mul_f32_e32 v207, v191, v207
	v_mul_f32_e32 v208, v191, v208
	v_mul_f32_e32 v209, v191, v209
	v_cvt_pk_bf16_f32 v206, v206, v207
	v_cvt_pk_bf16_f32 v207, v208, v209
	global_store_dwordx2 v[184:185], v[206:207], off offset:192
	v_mul_f32_e32 v210, v191, v210
	v_mul_f32_e32 v211, v191, v211
	v_mul_f32_e32 v212, v191, v212
	v_mul_f32_e32 v213, v191, v213
	v_cvt_pk_bf16_f32 v210, v210, v211
	v_cvt_pk_bf16_f32 v211, v212, v213
	global_store_dwordx2 v[184:185], v[210:211], off offset:224
	s_waitcnt vmcnt(12)
	s_barrier
	ds_read_b128 v[104:107], v179 offset:16384
	ds_read_b128 v[146:149], v179 offset:24576
	ds_read_b128 v[108:111], v179 offset:17408
	ds_read_b128 v[150:153], v179 offset:25600
	ds_read_b128 v[112:115], v179 offset:18432
	ds_read_b128 v[154:157], v179 offset:26624
	ds_read_b128 v[116:119], v179 offset:19456
	ds_read_b128 v[158:161], v179 offset:27648
	ds_read_b128 v[120:123], v179 offset:20480
	ds_read_b128 v[162:165], v179 offset:28672
	ds_read_b128 v[124:127], v179 offset:21504
	ds_read_b128 v[166:169], v179 offset:29696
	ds_read_b128 v[128:131], v179 offset:22528
	ds_read_b128 v[170:173], v179 offset:30720
	ds_read_b128 v[132:135], v179 offset:23552
	ds_read_b128 v[174:177], v179 offset:31744
	s_waitcnt lgkmcnt(14)
	v_mfma_f32_16x16x32_bf16 v[206:209], v[104:107], v[32:35], 0
	v_mfma_f32_16x16x32_bf16 v[210:213], v[146:149], v[32:35], 0
	s_waitcnt lgkmcnt(12)
	v_mfma_f32_16x16x32_bf16 v[206:209], v[108:111], v[40:43], v[206:209]
	v_mfma_f32_16x16x32_bf16 v[210:213], v[150:153], v[40:43], v[210:213]
	s_waitcnt lgkmcnt(10)
	v_mfma_f32_16x16x32_bf16 v[206:209], v[112:115], v[48:51], v[206:209]
	v_mfma_f32_16x16x32_bf16 v[210:213], v[154:157], v[48:51], v[210:213]
	s_waitcnt lgkmcnt(8)
	v_mfma_f32_16x16x32_bf16 v[206:209], v[116:119], v[56:59], v[206:209]
	v_mfma_f32_16x16x32_bf16 v[210:213], v[158:161], v[56:59], v[210:213]
	s_waitcnt lgkmcnt(6)
	v_mfma_f32_16x16x32_bf16 v[206:209], v[120:123], v[72:75], v[206:209]
	v_mfma_f32_16x16x32_bf16 v[210:213], v[162:165], v[72:75], v[210:213]
	s_waitcnt lgkmcnt(4)
	v_mfma_f32_16x16x32_bf16 v[206:209], v[124:127], v[80:83], v[206:209]
	v_mfma_f32_16x16x32_bf16 v[210:213], v[166:169], v[80:83], v[210:213]
	s_waitcnt lgkmcnt(2)
	v_mfma_f32_16x16x32_bf16 v[206:209], v[128:131], v[88:91], v[206:209]
	v_mfma_f32_16x16x32_bf16 v[210:213], v[170:173], v[88:91], v[210:213]
	s_waitcnt lgkmcnt(0)
	v_mfma_f32_16x16x32_bf16 v[206:209], v[132:135], v[96:99], v[206:209]
	v_mfma_f32_16x16x32_bf16 v[210:213], v[174:177], v[96:99], v[210:213]
	v_mul_f32_e32 v192, v191, v192
	v_mul_f32_e32 v193, v191, v193
	v_mul_f32_e32 v194, v191, v194
	v_mul_f32_e32 v195, v191, v195
	v_cvt_pk_bf16_f32 v192, v192, v193
	v_cvt_pk_bf16_f32 v193, v194, v195
	global_store_dwordx2 v[184:185], v[192:193], off offset:256
	v_mul_f32_e32 v196, v191, v196
	v_mul_f32_e32 v197, v191, v197
	v_mul_f32_e32 v198, v191, v198
	v_mul_f32_e32 v199, v191, v199
	v_cvt_pk_bf16_f32 v196, v196, v197
	v_cvt_pk_bf16_f32 v197, v198, v199
	global_store_dwordx2 v[184:185], v[196:197], off offset:288
	s_waitcnt vmcnt(12)
	s_barrier
; __device__ __forceinline__ unsigned cvt_pk_bf16(float lo, float hi) { unsigned r; asm volatile("v_cvt_pk_bf16_f32 %0, %1, %2" : "=v"(r) : "v"(lo), "v"(hi)); return r; }
; __device__ __forceinline__ f32x4 mfma16(bf16x8 a, bf16x8 b, f32x4 c) { return __builtin_amdgcn_mfma_f32_16x16x32_bf16(a, b, c, 0, 0, 0); }
; __device__ __forceinline__ void mem_task(bf16_t* zb, const bf16_t* kvm_b, const bf16_t* vmt_b, int hm, int t0, int lane, bool do_store) {
;     ...
;     for (int dt = 0; dt < 16; ++dt) {
;         if (dt + 2 < 16) { const bf16_t* vp = vbase + (size_t)((dt + 2) * 16) * 256;
; #pragma unroll
;             for (int kp = 0; kp < 8; ++kp) vfr[(dt + 2) % 3][kp] = *(const bf16x8*)(vp + kp * 32); }
;         f32x4 acc = zero4;
;         __builtin_amdgcn_s_setprio(1);
; #pragma unroll
;         for (int kp = 0; kp < 8; ++kp) acc = mfma16(vfr[dt % 3][kp], pf[kp], acc);
;         __builtin_amdgcn_s_setprio(0);
;         u32x2 w; w.x = cvt_pk_bf16(acc[0] * il, acc[1] * il); w.y = cvt_pk_bf16(acc[2] * il, acc[3] * il); if (do_store || acc[0] == 12345.678f) *(u32x2*)(qp + dt * 16 + 4 * fq) = w; }
	ds_read_b128 v[104:107], v179 offset:32768
	ds_read_b128 v[146:149], v179 offset:40960
	ds_read_b128 v[108:111], v179 offset:33792
	ds_read_b128 v[150:153], v179 offset:41984
	ds_read_b128 v[112:115], v179 offset:34816
	ds_read_b128 v[154:157], v179 offset:43008
	ds_read_b128 v[116:119], v179 offset:35840
	ds_read_b128 v[158:161], v179 offset:44032
	ds_read_b128 v[120:123], v179 offset:36864
	ds_read_b128 v[162:165], v179 offset:45056
	ds_read_b128 v[124:127], v179 offset:37888
	ds_read_b128 v[166:169], v179 offset:46080
	ds_read_b128 v[128:131], v179 offset:38912
	ds_read_b128 v[170:173], v179 offset:47104
	ds_read_b128 v[132:135], v179 offset:39936
	ds_read_b128 v[174:177], v179 offset:48128
	s_waitcnt lgkmcnt(14)
	v_mfma_f32_16x16x32_bf16 v[192:195], v[104:107], v[32:35], 0
	v_mfma_f32_16x16x32_bf16 v[196:199], v[146:149], v[32:35], 0
	s_waitcnt lgkmcnt(12)
	v_mfma_f32_16x16x32_bf16 v[192:195], v[108:111], v[40:43], v[192:195]
	v_mfma_f32_16x16x32_bf16 v[196:199], v[150:153], v[40:43], v[196:199]
	s_waitcnt lgkmcnt(10)
	v_mfma_f32_16x16x32_bf16 v[192:195], v[112:115], v[48:51], v[192:195]
	v_mfma_f32_16x16x32_bf16 v[196:199], v[154:157], v[48:51], v[196:199]
	s_waitcnt lgkmcnt(8)
	v_mfma_f32_16x16x32_bf16 v[192:195], v[116:119], v[56:59], v[192:195]
	v_mfma_f32_16x16x32_bf16 v[196:199], v[158:161], v[56:59], v[196:199]
	s_waitcnt lgkmcnt(6)
	v_mfma_f32_16x16x32_bf16 v[192:195], v[120:123], v[72:75], v[192:195]
	v_mfma_f32_16x16x32_bf16 v[196:199], v[162:165], v[72:75], v[196:199]
	s_waitcnt lgkmcnt(4)
	v_mfma_f32_16x16x32_bf16 v[192:195], v[124:127], v[80:83], v[192:195]
	v_mfma_f32_16x16x32_bf16 v[196:199], v[166:169], v[80:83], v[196:199]
	s_waitcnt lgkmcnt(2)
	v_mfma_f32_16x16x32_bf16 v[192:195], v[128:131], v[88:91], v[192:195]
	v_mfma_f32_16x16x32_bf16 v[196:199], v[170:173], v[88:91], v[196:199]
	s_waitcnt lgkmcnt(0)
	v_mfma_f32_16x16x32_bf16 v[192:195], v[132:135], v[96:99], v[192:195]
	v_mfma_f32_16x16x32_bf16 v[196:199], v[174:177], v[96:99], v[196:199]
	v_mul_f32_e32 v206, v191, v206
	v_mul_f32_e32 v207, v191, v207
	v_mul_f32_e32 v208, v191, v208
	v_mul_f32_e32 v209, v191, v209
	v_cvt_pk_bf16_f32 v206, v206, v207
	v_cvt_pk_bf16_f32 v207, v208, v209
	global_store_dwordx2 v[184:185], v[206:207], off offset:320
	v_mul_f32_e32 v210, v191, v210
	v_mul_f32_e32 v211, v191, v211
	v_mul_f32_e32 v212, v191, v212
	v_mul_f32_e32 v213, v191, v213
	v_cvt_pk_bf16_f32 v210, v210, v211
	v_cvt_pk_bf16_f32 v211, v212, v213
	global_store_dwordx2 v[184:185], v[210:211], off offset:352
	s_waitcnt vmcnt(12)
	s_barrier
	ds_read_b128 v[104:107], v179 offset:49152
	ds_read_b128 v[146:149], v179 offset:57344
	ds_read_b128 v[108:111], v179 offset:50176
	ds_read_b128 v[150:153], v179 offset:58368
	ds_read_b128 v[112:115], v179 offset:51200
	ds_read_b128 v[154:157], v179 offset:59392
	ds_read_b128 v[116:119], v179 offset:52224
	ds_read_b128 v[158:161], v179 offset:60416
	ds_read_b128 v[120:123], v179 offset:53248
	ds_read_b128 v[162:165], v179 offset:61440
	ds_read_b128 v[124:127], v179 offset:54272
	ds_read_b128 v[166:169], v179 offset:62464
	ds_read_b128 v[128:131], v179 offset:55296
	ds_read_b128 v[170:173], v179 offset:63488
	ds_read_b128 v[132:135], v179 offset:56320
	ds_read_b128 v[174:177], v179 offset:64512
	s_waitcnt lgkmcnt(14)
	v_mfma_f32_16x16x32_bf16 v[206:209], v[104:107], v[32:35], 0
	v_mfma_f32_16x16x32_bf16 v[210:213], v[146:149], v[32:35], 0
	s_waitcnt lgkmcnt(12)
	v_mfma_f32_16x16x32_bf16 v[206:209], v[108:111], v[40:43], v[206:209]
	v_mfma_f32_16x16x32_bf16 v[210:213], v[150:153], v[40:43], v[210:213]
	s_waitcnt lgkmcnt(10)
	v_mfma_f32_16x16x32_bf16 v[206:209], v[112:115], v[48:51], v[206:209]
	v_mfma_f32_16x16x32_bf16 v[210:213], v[154:157], v[48:51], v[210:213]
	s_waitcnt lgkmcnt(8)
	v_mfma_f32_16x16x32_bf16 v[206:209], v[116:119], v[56:59], v[206:209]
	v_mfma_f32_16x16x32_bf16 v[210:213], v[158:161], v[56:59], v[210:213]
	s_waitcnt lgkmcnt(6)
	v_mfma_f32_16x16x32_bf16 v[206:209], v[120:123], v[72:75], v[206:209]
	v_mfma_f32_16x16x32_bf16 v[210:213], v[162:165], v[72:75], v[210:213]
	s_waitcnt lgkmcnt(4)
	v_mfma_f32_16x16x32_bf16 v[206:209], v[124:127], v[80:83], v[206:209]
	v_mfma_f32_16x16x32_bf16 v[210:213], v[166:169], v[80:83], v[210:213]
	s_waitcnt lgkmcnt(2)
	v_mfma_f32_16x16x32_bf16 v[206:209], v[128:131], v[88:91], v[206:209]
	v_mfma_f32_16x16x32_bf16 v[210:213], v[170:173], v[88:91], v[210:213]
	s_waitcnt lgkmcnt(0)
	v_mfma_f32_16x16x32_bf16 v[206:209], v[132:135], v[96:99], v[206:209]
	v_mfma_f32_16x16x32_bf16 v[210:213], v[174:177], v[96:99], v[210:213]
	v_mul_f32_e32 v192, v191, v192
	v_mul_f32_e32 v193, v191, v193
	v_mul_f32_e32 v194, v191, v194
	v_mul_f32_e32 v195, v191, v195
	v_cvt_pk_bf16_f32 v192, v192, v193
	v_cvt_pk_bf16_f32 v193, v194, v195
	global_store_dwordx2 v[184:185], v[192:193], off offset:384
	v_mul_f32_e32 v196, v191, v196
	v_mul_f32_e32 v197, v191, v197
	v_mul_f32_e32 v198, v191, v198
	v_mul_f32_e32 v199, v191, v199
	v_cvt_pk_bf16_f32 v196, v196, v197
	v_cvt_pk_bf16_f32 v197, v198, v199
	global_store_dwordx2 v[184:185], v[196:197], off offset:416
	s_nop 7
	s_nop 7
	v_mul_f32_e32 v206, v191, v206
	v_mul_f32_e32 v207, v191, v207
	v_mul_f32_e32 v208, v191, v208
	v_mul_f32_e32 v209, v191, v209
	v_cvt_pk_bf16_f32 v206, v206, v207
	v_cvt_pk_bf16_f32 v207, v208, v209
	global_store_dwordx2 v[184:185], v[206:207], off offset:448
	v_mul_f32_e32 v210, v191, v210
	v_mul_f32_e32 v211, v191, v211
	v_mul_f32_e32 v212, v191, v212
	v_mul_f32_e32 v213, v191, v213
	v_cvt_pk_bf16_f32 v210, v210, v211
	v_cvt_pk_bf16_f32 v211, v212, v213
	global_store_dwordx2 v[184:185], v[210:211], off offset:480
	s_add_i32 s5, s5, s64
	s_cmpk_gt_i32 s5, 0x7ff
	s_cbranch_scc0 .LBB0_366
